# split-phase grid barrier for the 96 deferred WGs: arrive at G1 without waiting, start deferred FFN-in tiles at once, wait for G1 completion only before arriving at G2
# speedup vs baseline: 1.0301x; 1.0017x over previous
.LBB0_1314:
	s_lshl_b32 s4, s68, 8
	v_add_u32_e32 v172, s4, v151
	s_addk_i32 s4, 0xe000
	s_lshr_b32 s4, s4, 10
	s_add_i32 s4, s4, 1
	s_cmp_gt_i32 s68, 31
	s_cselect_b32 s4, s4, 0
	s_mul_hi_u32 s44, s4, 0x5800
	s_mulk_i32 s4, 0x5800
	s_add_u32 s4, s55, s4
	s_addc_u32 s48, s56, s44
	s_lshl_b32 s44, s67, 8
	s_ashr_i32 s45, s44, 31
	s_lshl_b64 s[44:45], s[44:45], 2
	v_ashrrev_i32_e32 v173, 31, v172
	s_add_u32 s4, s4, s44
	v_lshl_add_u64 v[130:131], v[172:173], 2, s[28:29]
	s_addc_u32 s45, s48, s45
	global_load_dword v148, v[130:131], off
	global_load_dword v149, v[130:131], off offset:64
	global_load_dword v150, v[130:131], off offset:128
	global_load_dword v152, v[130:131], off offset:192
	global_load_dword v154, v[130:131], off offset:512
	global_load_dword v156, v[130:131], off offset:576
	global_load_dword v158, v[130:131], off offset:640
	global_load_dword v163, v[130:131], off offset:704
	s_add_u32 s44, s4, s63
	s_addc_u32 s45, s45, 0
	global_load_dwordx4 v[164:167], v159, s[44:45] offset:512
	global_load_dwordx4 v[134:137], v159, s[44:45]
	global_load_dwordx4 v[168:171], v159, s[44:45] offset:528
	global_load_dwordx4 v[130:133], v159, s[44:45] offset:16
	v_mov_b32_e32 v194, v122
	v_mov_b32_e32 v177, v118
	v_mov_b32_e32 v118, v127
	v_mov_b32_e32 v196, v124
	v_or_b32_e32 v199, 48, v172
	v_mov_b32_e32 v176, v126
	v_mov_b32_e32 v193, v120
	v_mov_b32_e32 v120, v129
	v_mov_b32_e32 v192, v128
	v_mov_b32_e32 v195, v114
	v_mov_b32_e32 v197, v116
	v_mov_b32_e32 v116, v125
	v_mov_b32_e32 v114, v123
	v_lshl_or_b32 v174, s67, 7, v155
	v_ashrrev_i32_e32 v175, 31, v174
	v_or_b32_e32 v173, 16, v172
	v_or_b32_e32 v179, 32, v172
	v_add_u32_e32 v162, 0x80, v172
	v_add_u32_e32 v161, 0x90, v172
	v_add_u32_e32 v160, 0xa0, v172
	v_add_u32_e32 v123, 0xb0, v172
	s_and_b64 vcc, exec, s[6:7]
	s_mov_b64 s[6:7], -1
	s_waitcnt vmcnt(0)
	v_fmamk_f32 v122, v148, 0x3a800000, v227
	v_rsq_f32_e32 v198, v122
	v_fmamk_f32 v124, v149, 0x3a800000, v227
	v_fmamk_f32 v126, v152, 0x3a800000, v227
	v_fmamk_f32 v127, v154, 0x3a800000, v227
	v_fmamk_f32 v125, v150, 0x3a800000, v227
	v_fmamk_f32 v129, v158, 0x3a800000, v227
	v_fmamk_f32 v148, v163, 0x3a800000, v227
	v_mov_b32_e32 v149, v134
	v_mov_b32_e32 v134, v165
	v_rsq_f32_e32 v122, v148
	v_mov_b32_e32 v148, v164
	v_pk_fma_f32 v[118:119], v[118:119], v[198:199], v[134:135] op_sel_hi:[1,0,1]
	v_pk_fma_f32 v[164:165], v[176:177], v[198:199], v[148:149] op_sel_hi:[1,0,1]
	v_mul_f32_e32 v176, 0xbfb8aa3b, v119
	v_exp_f32_e32 v176, v176
	v_mul_f32_e32 v163, 0xbfb8aa3b, v165
	v_exp_f32_e32 v163, v163
	v_fmamk_f32 v128, v156, 0x3a800000, v227
	v_add_f32_e32 v176, 1.0, v176
	v_rcp_f32_e32 v176, v176
	v_rsq_f32_e32 v156, v126
	v_rsq_f32_e32 v154, v127
	v_rsq_f32_e32 v150, v129
	v_mov_b32_e32 v129, v136
	v_mov_b32_e32 v136, v167
	v_mov_b32_e32 v126, v168
	v_mov_b32_e32 v127, v130
	v_rsq_f32_e32 v152, v128
	v_mov_b32_e32 v128, v166
	v_mov_b32_e32 v130, v169
	v_pk_fma_f32 v[120:121], v[120:121], v[198:199], v[136:137] op_sel_hi:[1,0,1]
	v_pk_fma_f32 v[168:169], v[194:195], v[198:199], v[126:127] op_sel_hi:[1,0,1]
	v_mul_f32_e32 v119, v119, v176
	v_pk_fma_f32 v[166:167], v[192:193], v[198:199], v[128:129] op_sel_hi:[1,0,1]
	v_mul_f32_e32 v192, 0xbfb8aa3b, v121
	v_mul_f32_e32 v118, v118, v119
	v_mul_f32_e32 v119, 0xbfb8aa3b, v169
	v_mul_f32_e32 v177, 0xbfb8aa3b, v167
	v_exp_f32_e32 v192, v192
	v_add_f32_e32 v163, 1.0, v163
	v_exp_f32_e32 v119, v119
	v_exp_f32_e32 v177, v177
	v_rcp_f32_e32 v163, v163
	v_pk_fma_f32 v[114:115], v[114:115], v[198:199], v[130:131] op_sel_hi:[1,0,1]
	v_add_f32_e32 v192, 1.0, v192
	v_add_f32_e32 v119, 1.0, v119
	v_add_f32_e32 v177, 1.0, v177
	v_rcp_f32_e32 v192, v192
	v_mul_f32_e32 v163, v165, v163
	v_rcp_f32_e32 v119, v119
	v_mul_f32_e32 v165, 0xbfb8aa3b, v115
	v_rcp_f32_e32 v177, v177
	v_exp_f32_e32 v165, v165
	v_rsq_f32_e32 v200, v124
	v_rsq_f32_e32 v158, v125
	v_mov_b32_e32 v124, v170
	v_mov_b32_e32 v125, v132
	v_mov_b32_e32 v132, v171
	v_pk_fma_f32 v[170:171], v[196:197], v[198:199], v[124:125] op_sel_hi:[1,0,1]
	v_mul_f32_e32 v121, v121, v192
	v_mul_f32_e32 v119, v169, v119
	v_pk_fma_f32 v[116:117], v[116:117], v[198:199], v[132:133] op_sel_hi:[1,0,1]
	v_mul_f32_e32 v163, v164, v163
	v_mul_f32_e32 v164, v167, v177
	v_mul_f32_e32 v120, v120, v121
	v_mul_f32_e32 v121, v168, v119
	v_add_f32_e32 v119, 1.0, v165
	v_mul_f32_e32 v165, 0xbfb8aa3b, v171
	v_mul_f32_e32 v164, v166, v164
	v_rcp_f32_e32 v119, v119
	v_exp_f32_e32 v165, v165
	v_mul_f32_e32 v166, 0xbfb8aa3b, v117
	v_exp_f32_e32 v166, v166
	v_mul_f32_e32 v115, v115, v119
	v_add_f32_e32 v119, 1.0, v165
	v_rcp_f32_e32 v119, v119
	v_add_f32_e32 v165, 1.0, v166
	v_rcp_f32_e32 v165, v165
	v_mul_f32_e32 v114, v114, v115
	v_mul_f32_e32 v115, v171, v119
	v_mul_f32_e32 v115, v170, v115
	v_mul_f32_e32 v117, v117, v165
	v_mul_f32_e32 v116, v116, v117
	v_cvt_pk_bf16_f32 v118, v163, v118
	v_cvt_pk_bf16_f32 v119, v164, v120
	v_cvt_pk_bf16_f32 v120, v121, v114
	v_cvt_pk_bf16_f32 v121, v115, v116
	v_mov_b64_e32 v[114:115], s[26:27]
	v_mad_i64_i32 v[164:165], s[44:45], v172, s33, v[114:115]
	v_lshlrev_b64 v[116:117], 1, v[174:175]
	v_lshl_add_u64 v[164:165], v[164:165], 0, v[116:117]
	global_store_dwordx4 v[164:165], v[118:121], off
	s_nop 1
	v_mov_b32_e32 v118, v110
	v_mov_b32_e32 v119, v106
	v_pk_fma_f32 v[118:119], v[118:119], v[200:201], v[148:149] op_sel_hi:[1,0,1]
	v_mov_b32_e32 v106, v111
	v_pk_fma_f32 v[106:107], v[106:107], v[200:201], v[134:135] op_sel_hi:[1,0,1]
	v_mov_b32_e32 v111, v108
	v_mov_b32_e32 v108, v113
	v_mov_b32_e32 v113, v98
	v_mov_b32_e32 v98, v103
	v_mov_b32_e32 v103, v100
	v_mul_f32_e32 v100, 0xbfb8aa3b, v119
	v_mov_b32_e32 v110, v112
	v_mov_b32_e32 v112, v102
	v_mov_b32_e32 v102, v104
	v_exp_f32_e32 v104, v100
	v_mul_f32_e32 v100, 0xbfb8aa3b, v107
	v_exp_f32_e32 v120, v100
	v_mov_b32_e32 v100, v105
	v_add_f32_e32 v104, 1.0, v104
	v_rcp_f32_e32 v104, v104
	v_add_f32_e32 v105, 1.0, v120
	v_rcp_f32_e32 v105, v105
	v_pk_fma_f32 v[110:111], v[110:111], v[200:201], v[128:129] op_sel_hi:[1,0,1]
	v_pk_fma_f32 v[108:109], v[108:109], v[200:201], v[136:137] op_sel_hi:[1,0,1]
	v_mul_f32_e32 v104, v119, v104
	v_mul_f32_e32 v105, v107, v105
	v_mul_f32_e32 v107, 0xbfb8aa3b, v111
	v_mul_f32_e32 v104, v118, v104
	v_exp_f32_e32 v107, v107
	v_mul_f32_e32 v118, 0xbfb8aa3b, v109
	v_exp_f32_e32 v118, v118
	v_pk_fma_f32 v[112:113], v[112:113], v[200:201], v[126:127] op_sel_hi:[1,0,1]
	v_mul_f32_e32 v105, v106, v105
	v_add_f32_e32 v106, 1.0, v107
	v_rcp_f32_e32 v106, v106
	v_add_f32_e32 v107, 1.0, v118
	v_mul_f32_e32 v118, 0xbfb8aa3b, v113
	v_rcp_f32_e32 v107, v107
	v_exp_f32_e32 v118, v118
	v_pk_fma_f32 v[98:99], v[98:99], v[200:201], v[130:131] op_sel_hi:[1,0,1]
	v_mul_f32_e32 v106, v111, v106
	v_mul_f32_e32 v106, v110, v106
	v_mul_f32_e32 v107, v109, v107
	v_add_f32_e32 v109, 1.0, v118
	v_mul_f32_e32 v110, 0xbfb8aa3b, v99
	v_rcp_f32_e32 v109, v109
	v_exp_f32_e32 v110, v110
	v_pk_fma_f32 v[102:103], v[102:103], v[200:201], v[124:125] op_sel_hi:[1,0,1]
	v_pk_fma_f32 v[100:101], v[100:101], v[200:201], v[132:133] op_sel_hi:[1,0,1]
	v_mul_f32_e32 v107, v108, v107
	v_mul_f32_e32 v108, v113, v109
	v_add_f32_e32 v109, 1.0, v110
	v_mul_f32_e32 v110, 0xbfb8aa3b, v103
	v_rcp_f32_e32 v109, v109
	v_exp_f32_e32 v110, v110
	v_mul_f32_e32 v111, 0xbfb8aa3b, v101
	v_exp_f32_e32 v111, v111
	v_mul_f32_e32 v99, v99, v109
	v_add_f32_e32 v109, 1.0, v110
	v_rcp_f32_e32 v109, v109
	v_add_f32_e32 v110, 1.0, v111
	v_rcp_f32_e32 v110, v110
	v_mul_f32_e32 v111, v98, v99
	v_mul_f32_e32 v98, v103, v109
	v_mul_f32_e32 v102, v102, v98
	v_mul_f32_e32 v98, v101, v110
	v_mul_f32_e32 v101, v100, v98
	v_mul_f32_e32 v108, v112, v108
	v_cvt_pk_bf16_f32 v98, v104, v105
	v_cvt_pk_bf16_f32 v99, v106, v107
	v_cvt_pk_bf16_f32 v100, v108, v111
	v_cvt_pk_bf16_f32 v101, v102, v101
	v_mad_i64_i32 v[102:103], s[44:45], v173, s33, v[114:115]
	v_lshl_add_u64 v[102:103], v[102:103], 0, v[116:117]
	global_store_dwordx4 v[102:103], v[98:101], off
	s_nop 1
	v_mov_b32_e32 v98, v94
	v_mov_b32_e32 v99, v90
	v_pk_fma_f32 v[98:99], v[98:99], v[158:159], v[148:149] op_sel_hi:[1,0,1]
	v_mov_b32_e32 v90, v95
	v_pk_fma_f32 v[90:91], v[90:91], v[158:159], v[134:135] op_sel_hi:[1,0,1]
	v_mov_b32_e32 v95, v92
	v_mov_b32_e32 v92, v97
	v_mov_b32_e32 v97, v82
	v_mov_b32_e32 v82, v87
	v_mov_b32_e32 v87, v84
	v_mul_f32_e32 v84, 0xbfb8aa3b, v99
	v_mov_b32_e32 v94, v96
	v_mov_b32_e32 v96, v86
	v_mov_b32_e32 v86, v88
	v_exp_f32_e32 v88, v84
	v_mul_f32_e32 v84, 0xbfb8aa3b, v91
	v_exp_f32_e32 v100, v84
	v_mov_b32_e32 v84, v89
	v_add_f32_e32 v88, 1.0, v88
	v_rcp_f32_e32 v88, v88
	v_add_f32_e32 v89, 1.0, v100
	v_rcp_f32_e32 v89, v89
	v_pk_fma_f32 v[94:95], v[94:95], v[158:159], v[128:129] op_sel_hi:[1,0,1]
	v_pk_fma_f32 v[92:93], v[92:93], v[158:159], v[136:137] op_sel_hi:[1,0,1]
	v_mul_f32_e32 v88, v99, v88
	v_mul_f32_e32 v89, v91, v89
	v_mul_f32_e32 v91, 0xbfb8aa3b, v95
	v_mul_f32_e32 v88, v98, v88
	v_exp_f32_e32 v91, v91
	v_mul_f32_e32 v98, 0xbfb8aa3b, v93
	v_exp_f32_e32 v98, v98
	v_pk_fma_f32 v[96:97], v[96:97], v[158:159], v[126:127] op_sel_hi:[1,0,1]
	v_mul_f32_e32 v89, v90, v89
	v_add_f32_e32 v90, 1.0, v91
	v_rcp_f32_e32 v90, v90
	v_add_f32_e32 v91, 1.0, v98
	v_mul_f32_e32 v98, 0xbfb8aa3b, v97
	v_rcp_f32_e32 v91, v91
	v_exp_f32_e32 v98, v98
	v_pk_fma_f32 v[82:83], v[82:83], v[158:159], v[130:131] op_sel_hi:[1,0,1]
	v_mul_f32_e32 v90, v95, v90
	v_mul_f32_e32 v90, v94, v90
	v_mul_f32_e32 v91, v93, v91
	v_add_f32_e32 v93, 1.0, v98
	v_mul_f32_e32 v94, 0xbfb8aa3b, v83
	v_rcp_f32_e32 v93, v93
	v_exp_f32_e32 v94, v94
	v_pk_fma_f32 v[86:87], v[86:87], v[158:159], v[124:125] op_sel_hi:[1,0,1]
	v_pk_fma_f32 v[84:85], v[84:85], v[158:159], v[132:133] op_sel_hi:[1,0,1]
	v_mul_f32_e32 v91, v92, v91
	v_mul_f32_e32 v92, v97, v93
	v_add_f32_e32 v93, 1.0, v94
	v_mul_f32_e32 v94, 0xbfb8aa3b, v87
	v_rcp_f32_e32 v93, v93
	v_exp_f32_e32 v94, v94
	v_mul_f32_e32 v95, 0xbfb8aa3b, v85
	v_exp_f32_e32 v95, v95
	v_mul_f32_e32 v83, v83, v93
	v_add_f32_e32 v93, 1.0, v94
	v_rcp_f32_e32 v93, v93
	v_add_f32_e32 v94, 1.0, v95
	v_rcp_f32_e32 v94, v94
	v_mul_f32_e32 v95, v82, v83
	v_mul_f32_e32 v82, v87, v93
	v_mul_f32_e32 v86, v86, v82
	v_mul_f32_e32 v82, v85, v94
	v_mul_f32_e32 v85, v84, v82
	v_mul_f32_e32 v92, v96, v92
	v_cvt_pk_bf16_f32 v82, v88, v89
	v_cvt_pk_bf16_f32 v83, v90, v91
	v_cvt_pk_bf16_f32 v84, v92, v95
	v_cvt_pk_bf16_f32 v85, v86, v85
	v_mad_i64_i32 v[86:87], s[44:45], v179, s33, v[114:115]
	v_lshl_add_u64 v[86:87], v[86:87], 0, v[116:117]
	global_store_dwordx4 v[86:87], v[82:85], off
	s_nop 1
	v_mov_b32_e32 v82, v78
	v_mov_b32_e32 v83, v74
	v_pk_fma_f32 v[82:83], v[82:83], v[156:157], v[148:149] op_sel_hi:[1,0,1]
	v_mov_b32_e32 v74, v79
	v_pk_fma_f32 v[74:75], v[74:75], v[156:157], v[134:135] op_sel_hi:[1,0,1]
	v_mov_b32_e32 v79, v76
	v_mov_b32_e32 v76, v81
	v_mov_b32_e32 v81, v66
	v_mov_b32_e32 v66, v71
	v_mov_b32_e32 v71, v68
	v_mul_f32_e32 v68, 0xbfb8aa3b, v83
	v_mov_b32_e32 v78, v80
	v_mov_b32_e32 v80, v70
	v_mov_b32_e32 v70, v72
	v_exp_f32_e32 v72, v68
	v_mul_f32_e32 v68, 0xbfb8aa3b, v75
	v_exp_f32_e32 v84, v68
	v_mov_b32_e32 v68, v73
	v_add_f32_e32 v72, 1.0, v72
	v_rcp_f32_e32 v72, v72
	v_add_f32_e32 v73, 1.0, v84
	v_rcp_f32_e32 v73, v73
	v_pk_fma_f32 v[78:79], v[78:79], v[156:157], v[128:129] op_sel_hi:[1,0,1]
	v_pk_fma_f32 v[76:77], v[76:77], v[156:157], v[136:137] op_sel_hi:[1,0,1]
	v_mul_f32_e32 v72, v83, v72
	v_mul_f32_e32 v73, v75, v73
	v_mul_f32_e32 v75, 0xbfb8aa3b, v79
	v_mul_f32_e32 v72, v82, v72
	v_exp_f32_e32 v75, v75
	v_mul_f32_e32 v82, 0xbfb8aa3b, v77
	v_exp_f32_e32 v82, v82
	v_pk_fma_f32 v[80:81], v[80:81], v[156:157], v[126:127] op_sel_hi:[1,0,1]
	v_mul_f32_e32 v73, v74, v73
	v_add_f32_e32 v74, 1.0, v75
	v_rcp_f32_e32 v74, v74
	v_add_f32_e32 v75, 1.0, v82
	v_mul_f32_e32 v82, 0xbfb8aa3b, v81
	v_rcp_f32_e32 v75, v75
	v_exp_f32_e32 v82, v82
	v_pk_fma_f32 v[66:67], v[66:67], v[156:157], v[130:131] op_sel_hi:[1,0,1]
	v_mul_f32_e32 v74, v79, v74
	v_mul_f32_e32 v74, v78, v74
	v_mul_f32_e32 v75, v77, v75
	v_add_f32_e32 v77, 1.0, v82
	v_mul_f32_e32 v78, 0xbfb8aa3b, v67
	v_rcp_f32_e32 v77, v77
	v_exp_f32_e32 v78, v78
	v_pk_fma_f32 v[70:71], v[70:71], v[156:157], v[124:125] op_sel_hi:[1,0,1]
	v_pk_fma_f32 v[68:69], v[68:69], v[156:157], v[132:133] op_sel_hi:[1,0,1]
	v_mul_f32_e32 v75, v76, v75
	v_mul_f32_e32 v76, v81, v77
	v_add_f32_e32 v77, 1.0, v78
	v_mul_f32_e32 v78, 0xbfb8aa3b, v71
	v_rcp_f32_e32 v77, v77
	v_exp_f32_e32 v78, v78
	v_mul_f32_e32 v79, 0xbfb8aa3b, v69
	v_exp_f32_e32 v79, v79
	v_mul_f32_e32 v67, v67, v77
	v_add_f32_e32 v77, 1.0, v78
	v_rcp_f32_e32 v77, v77
	v_add_f32_e32 v78, 1.0, v79
	v_rcp_f32_e32 v78, v78
	v_mul_f32_e32 v79, v66, v67
	v_mul_f32_e32 v66, v71, v77
	v_mul_f32_e32 v70, v70, v66
	v_mul_f32_e32 v66, v69, v78
	v_mul_f32_e32 v69, v68, v66
	v_mul_f32_e32 v76, v80, v76
	v_cvt_pk_bf16_f32 v66, v72, v73
	v_cvt_pk_bf16_f32 v67, v74, v75
	v_cvt_pk_bf16_f32 v68, v76, v79
	v_cvt_pk_bf16_f32 v69, v70, v69
	v_mad_i64_i32 v[70:71], s[44:45], v199, s33, v[114:115]
	v_lshl_add_u64 v[70:71], v[70:71], 0, v[116:117]
	global_store_dwordx4 v[70:71], v[66:69], off
	s_nop 1
	v_mov_b32_e32 v66, v62
	v_mov_b32_e32 v67, v58
	v_pk_fma_f32 v[66:67], v[66:67], v[154:155], v[148:149] op_sel_hi:[1,0,1]
	v_mov_b32_e32 v58, v63
	v_pk_fma_f32 v[58:59], v[58:59], v[154:155], v[134:135] op_sel_hi:[1,0,1]
	v_mov_b32_e32 v63, v60
	v_mov_b32_e32 v60, v65
	v_mov_b32_e32 v65, v50
	v_mov_b32_e32 v50, v55
	v_mov_b32_e32 v55, v52
	v_mul_f32_e32 v52, 0xbfb8aa3b, v67
	v_mov_b32_e32 v62, v64
	v_mov_b32_e32 v64, v54
	v_mov_b32_e32 v54, v56
	v_exp_f32_e32 v56, v52
	v_mul_f32_e32 v52, 0xbfb8aa3b, v59
	v_exp_f32_e32 v68, v52
	v_mov_b32_e32 v52, v57
	v_add_f32_e32 v56, 1.0, v56
	v_rcp_f32_e32 v56, v56
	v_add_f32_e32 v57, 1.0, v68
	v_rcp_f32_e32 v57, v57
	v_pk_fma_f32 v[62:63], v[62:63], v[154:155], v[128:129] op_sel_hi:[1,0,1]
	v_pk_fma_f32 v[60:61], v[60:61], v[154:155], v[136:137] op_sel_hi:[1,0,1]
	v_mul_f32_e32 v56, v67, v56
	v_mul_f32_e32 v57, v59, v57
	v_mul_f32_e32 v59, 0xbfb8aa3b, v63
	v_mul_f32_e32 v56, v66, v56
	v_exp_f32_e32 v59, v59
	v_mul_f32_e32 v66, 0xbfb8aa3b, v61
	v_exp_f32_e32 v66, v66
	v_pk_fma_f32 v[64:65], v[64:65], v[154:155], v[126:127] op_sel_hi:[1,0,1]
	v_mul_f32_e32 v57, v58, v57
	v_add_f32_e32 v58, 1.0, v59
	v_rcp_f32_e32 v58, v58
	v_add_f32_e32 v59, 1.0, v66
	v_mul_f32_e32 v66, 0xbfb8aa3b, v65
	v_rcp_f32_e32 v59, v59
	v_exp_f32_e32 v66, v66
	v_pk_fma_f32 v[50:51], v[50:51], v[154:155], v[130:131] op_sel_hi:[1,0,1]
	v_mul_f32_e32 v58, v63, v58
	v_mul_f32_e32 v58, v62, v58
	v_mul_f32_e32 v59, v61, v59
	v_add_f32_e32 v61, 1.0, v66
	v_mul_f32_e32 v62, 0xbfb8aa3b, v51
	v_rcp_f32_e32 v61, v61
	v_exp_f32_e32 v62, v62
	v_pk_fma_f32 v[54:55], v[54:55], v[154:155], v[124:125] op_sel_hi:[1,0,1]
	v_pk_fma_f32 v[52:53], v[52:53], v[154:155], v[132:133] op_sel_hi:[1,0,1]
	v_mul_f32_e32 v59, v60, v59
	v_mul_f32_e32 v60, v65, v61
	v_add_f32_e32 v61, 1.0, v62
	v_mul_f32_e32 v62, 0xbfb8aa3b, v55
	v_rcp_f32_e32 v61, v61
	v_exp_f32_e32 v62, v62
	v_mul_f32_e32 v63, 0xbfb8aa3b, v53
	v_exp_f32_e32 v63, v63
	v_mul_f32_e32 v51, v51, v61
	v_add_f32_e32 v61, 1.0, v62
	v_rcp_f32_e32 v61, v61
	v_add_f32_e32 v62, 1.0, v63
	v_rcp_f32_e32 v62, v62
	v_mul_f32_e32 v63, v50, v51
	v_mul_f32_e32 v50, v55, v61
	v_mul_f32_e32 v54, v54, v50
	v_mul_f32_e32 v50, v53, v62
	v_mul_f32_e32 v53, v52, v50
	v_mul_f32_e32 v60, v64, v60
	v_cvt_pk_bf16_f32 v50, v56, v57
	v_cvt_pk_bf16_f32 v51, v58, v59
	v_cvt_pk_bf16_f32 v52, v60, v63
	v_cvt_pk_bf16_f32 v53, v54, v53
	v_mad_i64_i32 v[54:55], s[44:45], v162, s33, v[114:115]
	v_lshl_add_u64 v[54:55], v[54:55], 0, v[116:117]
	global_store_dwordx4 v[54:55], v[50:53], off
	s_nop 1
	v_mov_b32_e32 v50, v46
	v_mov_b32_e32 v51, v42
	v_pk_fma_f32 v[50:51], v[50:51], v[152:153], v[148:149] op_sel_hi:[1,0,1]
	v_mov_b32_e32 v42, v47
	v_pk_fma_f32 v[42:43], v[42:43], v[152:153], v[134:135] op_sel_hi:[1,0,1]
	v_mov_b32_e32 v47, v44
	v_mov_b32_e32 v44, v49
	v_mov_b32_e32 v49, v34
	v_mov_b32_e32 v34, v39
	v_mov_b32_e32 v39, v36
	v_mul_f32_e32 v36, 0xbfb8aa3b, v51
	v_mov_b32_e32 v46, v48
	v_mov_b32_e32 v48, v38
	v_mov_b32_e32 v38, v40
	v_exp_f32_e32 v40, v36
	v_mul_f32_e32 v36, 0xbfb8aa3b, v43
	v_exp_f32_e32 v52, v36
	v_mov_b32_e32 v36, v41
	v_add_f32_e32 v40, 1.0, v40
	v_rcp_f32_e32 v40, v40
	v_add_f32_e32 v41, 1.0, v52
	v_rcp_f32_e32 v41, v41
	v_pk_fma_f32 v[46:47], v[46:47], v[152:153], v[128:129] op_sel_hi:[1,0,1]
	v_pk_fma_f32 v[44:45], v[44:45], v[152:153], v[136:137] op_sel_hi:[1,0,1]
	v_mul_f32_e32 v40, v51, v40
	v_mul_f32_e32 v41, v43, v41
	v_mul_f32_e32 v43, 0xbfb8aa3b, v47
	v_mul_f32_e32 v40, v50, v40
	v_exp_f32_e32 v43, v43
	v_mul_f32_e32 v50, 0xbfb8aa3b, v45
	v_exp_f32_e32 v50, v50
	v_pk_fma_f32 v[48:49], v[48:49], v[152:153], v[126:127] op_sel_hi:[1,0,1]
	v_mul_f32_e32 v41, v42, v41
	v_add_f32_e32 v42, 1.0, v43
	v_rcp_f32_e32 v42, v42
	v_add_f32_e32 v43, 1.0, v50
	v_mul_f32_e32 v50, 0xbfb8aa3b, v49
	v_rcp_f32_e32 v43, v43
	v_exp_f32_e32 v50, v50
	v_pk_fma_f32 v[34:35], v[34:35], v[152:153], v[130:131] op_sel_hi:[1,0,1]
	v_mul_f32_e32 v42, v47, v42
	v_mul_f32_e32 v42, v46, v42
	v_mul_f32_e32 v43, v45, v43
	v_add_f32_e32 v45, 1.0, v50
	v_mul_f32_e32 v46, 0xbfb8aa3b, v35
	v_rcp_f32_e32 v45, v45
	v_exp_f32_e32 v46, v46
	v_pk_fma_f32 v[38:39], v[38:39], v[152:153], v[124:125] op_sel_hi:[1,0,1]
	v_pk_fma_f32 v[36:37], v[36:37], v[152:153], v[132:133] op_sel_hi:[1,0,1]
	v_mul_f32_e32 v43, v44, v43
	v_mul_f32_e32 v44, v49, v45
	v_add_f32_e32 v45, 1.0, v46
	v_mul_f32_e32 v46, 0xbfb8aa3b, v39
	v_rcp_f32_e32 v45, v45
	v_exp_f32_e32 v46, v46
	v_mul_f32_e32 v47, 0xbfb8aa3b, v37
	v_exp_f32_e32 v47, v47
	v_mul_f32_e32 v35, v35, v45
	v_add_f32_e32 v45, 1.0, v46
	v_rcp_f32_e32 v45, v45
	v_add_f32_e32 v46, 1.0, v47
	v_rcp_f32_e32 v46, v46
	v_mul_f32_e32 v47, v34, v35
	v_mul_f32_e32 v34, v39, v45
	v_mul_f32_e32 v38, v38, v34
	v_mul_f32_e32 v34, v37, v46
	v_mul_f32_e32 v37, v36, v34
	v_mul_f32_e32 v44, v48, v44
	v_cvt_pk_bf16_f32 v34, v40, v41
	v_cvt_pk_bf16_f32 v35, v42, v43
	v_cvt_pk_bf16_f32 v36, v44, v47
	v_cvt_pk_bf16_f32 v37, v38, v37
	v_mad_i64_i32 v[38:39], s[44:45], v161, s33, v[114:115]
	v_lshl_add_u64 v[38:39], v[38:39], 0, v[116:117]
	global_store_dwordx4 v[38:39], v[34:37], off
	s_nop 1
	v_mov_b32_e32 v34, v30
	v_mov_b32_e32 v35, v26
	v_pk_fma_f32 v[34:35], v[34:35], v[150:151], v[148:149] op_sel_hi:[1,0,1]
	v_mov_b32_e32 v26, v31
	v_pk_fma_f32 v[26:27], v[26:27], v[150:151], v[134:135] op_sel_hi:[1,0,1]
	v_mov_b32_e32 v31, v28
	v_mov_b32_e32 v28, v33
	v_mov_b32_e32 v33, v18
	v_mov_b32_e32 v18, v23
	v_mov_b32_e32 v23, v20
	v_mul_f32_e32 v20, 0xbfb8aa3b, v35
	v_mov_b32_e32 v30, v32
	v_mov_b32_e32 v32, v22
	v_mov_b32_e32 v22, v24
	v_exp_f32_e32 v24, v20
	v_mul_f32_e32 v20, 0xbfb8aa3b, v27
	v_exp_f32_e32 v36, v20
	v_mov_b32_e32 v20, v25
	v_add_f32_e32 v24, 1.0, v24
	v_rcp_f32_e32 v24, v24
	v_add_f32_e32 v25, 1.0, v36
	v_rcp_f32_e32 v25, v25
	v_pk_fma_f32 v[30:31], v[30:31], v[150:151], v[128:129] op_sel_hi:[1,0,1]
	v_pk_fma_f32 v[28:29], v[28:29], v[150:151], v[136:137] op_sel_hi:[1,0,1]
	v_mul_f32_e32 v24, v35, v24
	v_mul_f32_e32 v25, v27, v25
	v_mul_f32_e32 v27, 0xbfb8aa3b, v31
	v_mul_f32_e32 v24, v34, v24
	v_exp_f32_e32 v27, v27
	v_mul_f32_e32 v34, 0xbfb8aa3b, v29
	v_exp_f32_e32 v34, v34
	v_pk_fma_f32 v[32:33], v[32:33], v[150:151], v[126:127] op_sel_hi:[1,0,1]
	v_mul_f32_e32 v25, v26, v25
	v_add_f32_e32 v26, 1.0, v27
	v_rcp_f32_e32 v26, v26
	v_add_f32_e32 v27, 1.0, v34
	v_mul_f32_e32 v34, 0xbfb8aa3b, v33
	v_rcp_f32_e32 v27, v27
	v_exp_f32_e32 v34, v34
	v_pk_fma_f32 v[18:19], v[18:19], v[150:151], v[130:131] op_sel_hi:[1,0,1]
	v_mul_f32_e32 v26, v31, v26
	v_mul_f32_e32 v26, v30, v26
	v_mul_f32_e32 v27, v29, v27
	v_add_f32_e32 v29, 1.0, v34
	v_mul_f32_e32 v30, 0xbfb8aa3b, v19
	v_rcp_f32_e32 v29, v29
	v_exp_f32_e32 v30, v30
	v_pk_fma_f32 v[22:23], v[22:23], v[150:151], v[124:125] op_sel_hi:[1,0,1]
	v_pk_fma_f32 v[20:21], v[20:21], v[150:151], v[132:133] op_sel_hi:[1,0,1]
	v_mul_f32_e32 v27, v28, v27
	v_mul_f32_e32 v28, v33, v29
	v_add_f32_e32 v29, 1.0, v30
	v_mul_f32_e32 v30, 0xbfb8aa3b, v23
	v_rcp_f32_e32 v29, v29
	v_exp_f32_e32 v30, v30
	v_mul_f32_e32 v31, 0xbfb8aa3b, v21
	v_exp_f32_e32 v31, v31
	v_mul_f32_e32 v19, v19, v29
	v_add_f32_e32 v29, 1.0, v30
	v_rcp_f32_e32 v29, v29
	v_add_f32_e32 v30, 1.0, v31
	v_rcp_f32_e32 v30, v30
	v_mul_f32_e32 v31, v18, v19
	v_mul_f32_e32 v18, v23, v29
	v_mul_f32_e32 v22, v22, v18
	v_mul_f32_e32 v18, v21, v30
	v_mul_f32_e32 v21, v20, v18
	v_mul_f32_e32 v28, v32, v28
	v_cvt_pk_bf16_f32 v18, v24, v25
	v_cvt_pk_bf16_f32 v19, v26, v27
	v_cvt_pk_bf16_f32 v20, v28, v31
	v_cvt_pk_bf16_f32 v21, v22, v21
	v_mad_i64_i32 v[22:23], s[44:45], v160, s33, v[114:115]
	v_lshl_add_u64 v[22:23], v[22:23], 0, v[116:117]
	global_store_dwordx4 v[22:23], v[18:21], off
	s_nop 1
	v_mov_b32_e32 v18, v14
	v_mov_b32_e32 v19, v10
	v_pk_fma_f32 v[18:19], v[18:19], v[122:123], v[148:149] op_sel_hi:[1,0,1]
	v_mov_b32_e32 v10, v15
	v_mov_b32_e32 v15, v12
	v_mov_b32_e32 v12, v17
	v_mov_b32_e32 v17, v6
	v_mov_b32_e32 v6, v3
	v_pk_fma_f32 v[10:11], v[10:11], v[122:123], v[134:135] op_sel_hi:[1,0,1]
	v_mov_b32_e32 v14, v16
	v_mov_b32_e32 v16, v2
	v_pk_fma_f32 v[2:3], v[6:7], v[122:123], v[130:131] op_sel_hi:[1,0,1]
	v_mov_b32_e32 v6, v4
	v_mul_f32_e32 v4, 0xbfb8aa3b, v19
	v_mov_b32_e32 v7, v8
	v_exp_f32_e32 v4, v4
	v_mul_f32_e32 v8, 0xbfb8aa3b, v11
	v_exp_f32_e32 v20, v8
	v_pk_fma_f32 v[14:15], v[14:15], v[122:123], v[128:129] op_sel_hi:[1,0,1]
	v_add_f32_e32 v4, 1.0, v4
	v_rcp_f32_e32 v21, v4
	v_add_f32_e32 v4, 1.0, v20
	v_rcp_f32_e32 v20, v4
	v_mov_b32_e32 v8, v5
	v_pk_fma_f32 v[12:13], v[12:13], v[122:123], v[136:137] op_sel_hi:[1,0,1]
	v_pk_fma_f32 v[4:5], v[8:9], v[122:123], v[132:133] op_sel_hi:[1,0,1]
	v_mul_f32_e32 v8, v19, v21
	v_mul_f32_e32 v9, v11, v20
	v_mul_f32_e32 v11, 0xbfb8aa3b, v15
	v_mul_f32_e32 v8, v18, v8
	v_exp_f32_e32 v11, v11
	v_mul_f32_e32 v18, 0xbfb8aa3b, v13
	v_exp_f32_e32 v18, v18
	v_pk_fma_f32 v[16:17], v[16:17], v[122:123], v[126:127] op_sel_hi:[1,0,1]
	v_mul_f32_e32 v9, v10, v9
	v_add_f32_e32 v10, 1.0, v11
	v_rcp_f32_e32 v10, v10
	v_add_f32_e32 v11, 1.0, v18
	v_mul_f32_e32 v18, 0xbfb8aa3b, v17
	v_rcp_f32_e32 v11, v11
	v_exp_f32_e32 v18, v18
	v_mul_f32_e32 v10, v15, v10
	v_mul_f32_e32 v10, v14, v10
	v_mul_f32_e32 v11, v13, v11
	v_add_f32_e32 v13, 1.0, v18
	v_mul_f32_e32 v14, 0xbfb8aa3b, v3
	v_rcp_f32_e32 v13, v13
	v_exp_f32_e32 v14, v14
	v_pk_fma_f32 v[6:7], v[6:7], v[122:123], v[124:125] op_sel_hi:[1,0,1]
	v_mul_f32_e32 v11, v12, v11
	v_mul_f32_e32 v12, v17, v13
	v_add_f32_e32 v13, 1.0, v14
	v_mul_f32_e32 v14, 0xbfb8aa3b, v7
	v_rcp_f32_e32 v13, v13
	v_exp_f32_e32 v14, v14
	v_mul_f32_e32 v15, 0xbfb8aa3b, v5
	v_exp_f32_e32 v15, v15
	v_mul_f32_e32 v3, v3, v13
	v_add_f32_e32 v13, 1.0, v14
	v_rcp_f32_e32 v13, v13
	v_add_f32_e32 v14, 1.0, v15
	v_rcp_f32_e32 v14, v14
	v_mul_f32_e32 v15, v2, v3
	v_mul_f32_e32 v2, v7, v13
	v_mul_f32_e32 v6, v6, v2
	v_mul_f32_e32 v2, v5, v14
	v_mul_f32_e32 v5, v4, v2
	v_mul_f32_e32 v12, v16, v12
	v_cvt_pk_bf16_f32 v2, v8, v9
	v_cvt_pk_bf16_f32 v3, v10, v11
	v_cvt_pk_bf16_f32 v4, v12, v15
	v_cvt_pk_bf16_f32 v5, v6, v5
	v_mad_i64_i32 v[6:7], s[44:45], v123, s33, v[114:115]
	v_lshl_add_u64 v[6:7], v[6:7], 0, v[116:117]
	global_store_dwordx4 v[6:7], v[2:5], off
	s_cmp_eq_u32 s100, 0
	s_cbranch_scc1 .Lko_nog
	s_cmp_lg_u32 s62, 3
	s_cbranch_scc1 .Lko_nog
	s_cmp_lt_u32 s2, 0xa0
	s_cbranch_scc1 .Lko_nog
	s_mov_b32 s4, 0
	s_nop 2
	v_writelane_b32 v255, s4, 61
	v_writelane_b32 v255, s8, 1
	v_writelane_b32 v255, s9, 2
	v_writelane_b32 v255, s10, 3
	v_writelane_b32 v255, s11, 4
	v_writelane_b32 v255, s12, 5
	v_writelane_b32 v255, s13, 6
	v_writelane_b32 v255, s22, 7
	v_writelane_b32 v255, s24, 8
	v_writelane_b32 v255, s25, 9
	v_writelane_b32 v255, s26, 10
	v_writelane_b32 v255, s27, 11
	v_writelane_b32 v255, s28, 12
	v_writelane_b32 v255, s29, 13
	v_writelane_b32 v255, s30, 14
	v_writelane_b32 v255, s31, 15
	v_writelane_b32 v255, s36, 16
	v_writelane_b32 v255, s37, 17
	v_writelane_b32 v255, s38, 18
	v_writelane_b32 v255, s39, 19
	v_writelane_b32 v255, s40, 20
	v_writelane_b32 v255, s41, 21
	v_writelane_b32 v255, s42, 22
	v_writelane_b32 v255, s43, 23
	v_writelane_b32 v255, s52, 24
	v_writelane_b32 v255, s53, 25
	v_writelane_b32 v255, s70, 26
	v_writelane_b32 v255, s71, 27
	v_writelane_b32 v255, s74, 28
	v_writelane_b32 v255, s75, 29
	v_writelane_b32 v255, s76, 30
	v_writelane_b32 v255, s77, 31
	v_writelane_b32 v255, s78, 32
	v_writelane_b32 v255, s79, 33
	v_writelane_b32 v255, s82, 34
	v_writelane_b32 v255, s83, 35
	v_writelane_b32 v255, s84, 36
	v_writelane_b32 v255, s85, 37
	v_writelane_b32 v255, s90, 38
	v_writelane_b32 v255, s91, 39
	v_writelane_b32 v255, s92, 40
	v_writelane_b32 v255, s93, 41
	v_writelane_b32 v255, s94, 42
	v_writelane_b32 v255, s95, 43
	v_writelane_b32 v255, s96, 44
	v_writelane_b32 v255, s97, 45
	v_writelane_b32 v255, vcc_lo, 46
	v_writelane_b32 v255, vcc_hi, 47
	v_mov_b32_e32 v200, v0
	v_mov_b32_e32 v201, v2
	v_mov_b32_e32 v202, v3
	v_mov_b32_e32 v203, v4
	v_mov_b32_e32 v204, v5
	v_mov_b32_e32 v205, v6
	v_mov_b32_e32 v206, v7
	v_mov_b32_e32 v207, v8
	v_mov_b32_e32 v208, v9
	v_mov_b32_e32 v209, v10
	v_mov_b32_e32 v210, v11
	v_mov_b32_e32 v211, v12
	v_mov_b32_e32 v212, v13
	v_mov_b32_e32 v213, v14
	v_mov_b32_e32 v214, v15
	v_mov_b32_e32 v215, v16
	v_mov_b32_e32 v216, v17
	s_mov_b64 s[10:11], s[0:1]
	s_getreg_b32 s4, hwreg(HW_REG_XCC_ID, 0, 4)
	s_waitcnt vmcnt(0)
	s_waitcnt lgkmcnt(0)
	s_barrier
	s_and_saveexec_b64 s[8:9], s[78:79]
	s_cbranch_execz .Lko_g1440
	v_readlane_b32 s12, v253, 60
	s_load_dwordx2 s[10:11], s[10:11], 0xe0
	s_waitcnt vmcnt(0) expcnt(0) lgkmcnt(0)
	v_mov_b32_e32 v0, s12
	ds_read_b32 v3, v0
	v_readlane_b32 s12, v253, 61
	s_and_b32 s4, s4, 15
	s_waitcnt lgkmcnt(0)
	v_cmp_ne_u32_e32 vcc, 0, v3
	v_mov_b32_e32 v0, s12
	ds_read_b32 v2, v0
	s_cbranch_vccnz .Lko_g1404
	s_add_u32 s12, s10, 0x4200
	s_addc_u32 s13, s11, 0
	s_add_u32 s24, s10, 0x4400
	s_addc_u32 s25, s11, 0
	s_add_u32 s26, s10, 0x4500
	s_addc_u32 s27, s11, 0
	s_add_u32 s28, s10, 0x4600
	s_addc_u32 s29, s11, 0
	s_add_u32 s36, s10, 0x4700
	s_addc_u32 s37, s11, 0
	s_add_u32 s40, s10, 0x4800
	s_addc_u32 s41, s11, 0
	s_add_u32 s42, s10, 0x4900
	s_addc_u32 s43, s11, 0
	s_add_u32 s44, s10, 0x4a00
	s_addc_u32 s45, s11, 0
	s_add_u32 s48, s10, 0x4b00
	s_addc_u32 s49, s11, 0
	s_add_u32 s52, s10, 0x4c00
	s_addc_u32 s53, s11, 0
	s_add_u32 s70, s10, 0x4d00
	s_addc_u32 s71, s11, 0
	s_add_u32 s74, s10, 0x4e00
	s_addc_u32 s75, s11, 0
	s_add_u32 s76, s10, 0x4f00
	s_addc_u32 s77, s11, 0
	s_add_u32 s78, s10, 0x5000
	s_addc_u32 s79, s11, 0
	s_add_u32 s82, s10, 0x5100
	s_addc_u32 s83, s11, 0
	s_add_u32 s90, s10, 0x5200
	s_addc_u32 s91, s11, 0
	s_add_u32 s92, s10, 0x5300
	s_addc_u32 s93, s11, 0
	s_mov_b32 s22, 1
	s_branch .Lko_g1392

.Lko_g1406:
	s_or_b64 exec, exec, s[26:27]
	v_cvt_f32_u32_e32 v5, v3
	s_waitcnt vmcnt(0)
	v_readfirstlane_b32 s4, v4
	v_sub_u32_e32 v4, 0, v3
	v_rcp_iflag_f32_e32 v5, v5
	v_add_u32_e32 v6, s4, v0
	v_mul_f32_e32 v5, 0x4f7ffffe, v5
	v_cvt_u32_f32_e32 v5, v5
	v_mul_lo_u32 v0, v4, v5
	v_mul_hi_u32 v0, v5, v0
	v_add_u32_e32 v0, v5, v0
	v_mul_hi_u32 v0, v6, v0
	v_mul_lo_u32 v4, v0, v3
	v_sub_u32_e32 v4, v6, v4
	v_add_u32_e32 v5, 1, v0
	v_cmp_ge_u32_e32 vcc, v4, v3
	s_nop 1
	v_cndmask_b32_e32 v0, v0, v5, vcc
	v_sub_u32_e32 v5, v4, v3
	v_cndmask_b32_e32 v4, v4, v5, vcc
	v_add_u32_e32 v5, 1, v0
	v_cmp_ge_u32_e32 vcc, v4, v3
	v_add_u32_e32 v4, 1, v6
	s_nop 0
	v_cndmask_b32_e32 v0, v0, v5, vcc
	v_mul_lo_u32 v5, v3, v0
	v_add_u32_e32 v3, v5, v3
	v_cmp_ne_u32_e32 vcc, v4, v3
	s_and_saveexec_b64 s[24:25], vcc
	s_xor_b64 s[24:25], exec, s[24:25]
	s_cbranch_execz .Lko_g1420
	v_readfirstlane_b32 s22, v0
	s_mov_b32 s26, 1
	s_nop 2
	v_writelane_b32 v255, s22, 60
	v_writelane_b32 v255, s26, 61
	s_nop 1

.Lko_g1_skip:
	s_mov_b64 s[8:9], s[0:1]
	s_waitcnt lgkmcnt(0)
	s_barrier
	s_branch .Lko_w_after
.Lko_w_entry:
	s_and_saveexec_b64 s[8:9], s[78:79]
	s_cbranch_execz .Lko_w_done
	v_readlane_b32 s22, v255, 61
	v_readlane_b32 s24, v255, 60
	s_cmp_eq_u32 s22, 0
	s_cbranch_scc1 .Lko_w_done
	s_load_dwordx2 s[12:13], s[0:1], 0xe0
	s_and_b32 s25, s4, 15
	s_lshl_b32 s25, s25, 8
	s_add_i32 s25, s25, 0x6400
	v_mov_b32_e32 v2, 0
	s_mov_b32 s26, 0
	s_waitcnt lgkmcnt(0)
	s_add_u32 s12, s12, s25
	s_addc_u32 s13, s13, 0
.Lko_w_spin:
	global_load_dword v3, v2, s[12:13] sc1
	s_waitcnt vmcnt(0)
	v_readfirstlane_b32 s27, v3
	s_cmp_lg_u32 s27, s24
	s_cbranch_scc1 .Lko_w_done
	s_sleep 1
	s_add_i32 s26, s26, 1
	s_cmp_lt_u32 s26, 0x40000
	s_cbranch_scc1 .Lko_w_spin
.Lko_w_done:
	s_or_b64 exec, exec, s[8:9]
	s_branch .Lko_g1_skip
.Lko_w_after:
	s_load_dwordx2 s[48:49], s[8:9], 0xe0
	s_mov_b64 s[8:9], s[0:1]
	s_load_dwordx2 s[44:45], s[8:9], 0xe0
	v_readlane_b32 s8, v254, 34
	v_readlane_b32 s10, v254, 60
	v_readlane_b32 s9, v254, 35
	v_readlane_b32 s11, v254, 61
	s_and_b64 s[8:9], s[8:9], s[10:11]
	s_mov_b64 s[24:25], 0
	s_and_b64 vcc, exec, s[8:9]
	s_cbranch_vccnz .LBB0_1450
	s_mov_b64 s[10:11], -1
	s_and_b64 vcc, exec, s[14:15]
	s_cbranch_vccz .LBB0_1443
	s_mov_b64 s[8:9], s[0:1]
	s_mov_b64 s[10:11], 0
